# attention work queue: next unit's ticket (atomic) fetched while the current unit runs
# baseline (speedup 1.0000x reference)
; __device__ __forceinline__ void attn_phase(const Args& a, unsigned char* lds_generic) {
;     ...
;       offs[2 * tid] = base; offs[2 * tid + 1] = base + c0; if (tid == 511) offs[1024] = base + mine;
;       __syncthreads(); }
;     const int nsel = offs[1024], FOXN = (EXP == 10 ? 2048 : 1024), total = FOXN + nsel;
;     const int* TMIN = (const int*)(ws + WS_LEN) + 1024; unsigned* qctr = (unsigned*)ws + 3600;
;     for (;;) {
;         int qo_ = 1048; asm volatile("" : "+s"(qo_)); lds_int* qslot = offs + qo_;
;         int tl_ = tid; asm volatile("" : "+v"(tl_)); const int r32 = tl_ & 31; const int wid = __builtin_amdgcn_readfirstlane(tl_ >> 6);
;         if (tid == 0) qslot[0] = (int)__hip_atomic_fetch_add(qctr, 1u, __ATOMIC_RELAXED, __HIP_MEMORY_SCOPE_AGENT);
.LBB0_725:
	v_lshl_add_u32 v0, v0, 2, 0
	s_movk_i32 s3, 0x1ff
	s_mov_b32 s7, 0
	v_add_u32_e32 v0, 0x1cc00, v0
	v_add_u32_e32 v3, v2, v8
	v_cmp_eq_u32_e32 vcc, s3, v216
	ds_write_b64 v0, v[2:3]
	s_and_saveexec_b64 s[8:9], vcc
	s_add_i32 s3, 0, 0x1dc00
	v_add_u32_e32 v0, v2, v1
	v_mov_b32_e32 v1, s3
	ds_write_b32 v1, v0
	s_or_b64 exec, exec, s[8:9]
	s_add_u32 s3, s46, 0xfc00000
	s_addc_u32 s28, s47, 0
	s_add_u32 s29, s46, 0x17c00000
	s_addc_u32 s30, s47, 0
	s_add_u32 s48, s46, 0xbc00000
	s_addc_u32 s49, s47, 0
	s_add_u32 s31, s46, 0x13c00000
	s_addc_u32 s34, s47, 0
	s_add_u32 s50, s46, 0x1e600000
	s_addc_u32 s51, s47, 0
	s_add_u32 s35, s46, 0x1c600000
	s_addc_u32 s36, s47, 0
	s_add_i32 s6, 0, 0x1dc00
	s_add_u32 s52, s46, 0x1eb01000
	v_mov_b32_e32 v0, s6
	s_addc_u32 s53, s47, 0
	s_waitcnt lgkmcnt(0)
	s_barrier
	ds_read_b32 v0, v0
	s_add_u32 s54, s46, 0x3840
	s_addc_u32 s55, s47, 0
	s_add_u32 s56, s46, 0x50100
	s_addc_u32 s57, s47, 0
	s_add_u32 s37, s46, 0x5900000
	s_waitcnt lgkmcnt(0)
	v_add_u32_e32 v217, 0x400, v0
	v_cmp_eq_u32_e64 s[38:39], 0, v216
	s_addc_u32 s64, s47, 0
	v_mov_b32_e32 v209, 0
	s_mov_b64 s[46:47], 0x20000
	s_mov_b64 s[58:59], 0x40000
	s_mov_b64 s[60:61], 0x60000
	s_mov_b32 s65, 0x41000000
	s_mov_b64 s[62:63], 0x400
	s_add_i32 s66, 0, 0x14e00
	v_mov_b32_e32 v218, 0x42000000
	v_mov_b32_e32 v219, 0xff800000
	s_and_saveexec_b64 s[98:99], s[38:39]
	s_cbranch_execz .Lq_first_skip
	v_mov_b32_e32 v237, 1
	global_atomic_add v237, v209, v237, s[54:55] sc0
.Lq_first_skip:
	s_or_b64 exec, exec, s[98:99]
	s_branch .LBB0_731

; __device__ __forceinline__ void attn_phase(const Args& a, unsigned char* lds_generic) {
;     ...
;         int qo_ = 1048; asm volatile("" : "+s"(qo_)); lds_int* qslot = offs + qo_;
;         int tl_ = tid; asm volatile("" : "+v"(tl_)); const int r32 = tl_ & 31; const int wid = __builtin_amdgcn_readfirstlane(tl_ >> 6);
;         if (tid == 0) qslot[0] = (int)__hip_atomic_fetch_add(qctr, 1u, __ATOMIC_RELAXED, __HIP_MEMORY_SCOPE_AGENT);
;         __syncthreads();
;         const int idx = qslot[0];
.LBB0_731:
	s_movk_i32 s6, 0x418
	s_lshl_b32 s6, s6, 2
	s_add_i32 s14, s6, 0
	v_mov_b32_e32 v0, v216
	s_add_i32 s14, s14, 0x1cc00
	s_nop 0
	v_readfirstlane_b32 s6, v0
	s_and_saveexec_b64 s[10:11], s[38:39]
	s_cbranch_execz .LBB0_735
	s_mov_b64 s[12:13], exec
	v_mbcnt_lo_u32_b32 v1, s12, 0
	v_mbcnt_hi_u32_b32 v1, s13, v1
	v_cmp_eq_u32_e32 vcc, 0, v1
	s_and_saveexec_b64 s[8:9], vcc
	s_cbranch_execz .LBB0_734
	s_bcnt1_i32_b64 s12, s[12:13]
	s_waitcnt vmcnt(0)
	v_mov_b32_e32 v2, v237
	v_mov_b32_e32 v237, s12
	global_atomic_add v237, v209, v237, s[54:55] sc0
.LBB0_734:
	s_or_b64 exec, exec, s[8:9]
	v_readfirstlane_b32 s8, v2
	v_mov_b32_e32 v2, s14
	s_nop 0
	v_add_u32_e32 v1, s8, v1
	ds_write_b32 v2, v1
